# barrier: b6 + non-last XCD leaders poll the TOP arrival counter directly instead of waiting for TOPGEN
# speedup vs baseline: 1.0038x; 1.0003x over previous
.LBB0_261:
	s_or_b64 exec, exec, s[10:11]
	v_cvt_f32_u32_e32 v3, v0
	s_waitcnt vmcnt(0)
	v_readfirstlane_b32 s6, v2
	s_add_u32 s10, s26, 0xfe03500
	s_addc_u32 s11, s27, 0
	v_rcp_iflag_f32_e32 v3, v3
	v_add_u32_e32 v1, s6, v1
	v_add_u32_e32 v4, 1, v1
	s_mov_b64 s[12:13], -1
	v_mul_f32_e32 v2, 0x4f7ffffe, v3
	v_cvt_u32_f32_e32 v2, v2
	v_sub_u32_e32 v3, 0, v0
	v_mul_lo_u32 v3, v3, v2
	v_mul_hi_u32 v3, v2, v3
	v_add_u32_e32 v2, v2, v3
	v_mul_hi_u32 v2, v1, v2
	v_mul_lo_u32 v3, v2, v0
	v_sub_u32_e32 v1, v1, v3
	v_add_u32_e32 v5, 1, v2
	v_cmp_ge_u32_e32 vcc, v1, v0
	v_sub_u32_e32 v3, v1, v0
	s_nop 0
	v_cndmask_b32_e32 v2, v2, v5, vcc
	v_cndmask_b32_e32 v1, v1, v3, vcc
	v_add_u32_e32 v3, 1, v2
	v_cmp_ge_u32_e32 vcc, v1, v0
	s_nop 1
	v_cndmask_b32_e32 v2, v2, v3, vcc
	v_mul_lo_u32 v1, v0, v2
	v_add_u32_e32 v0, v1, v0
	v_cmp_ne_u32_e32 vcc, v4, v0
	v_mov_b32_e32 v34, v0
	v_mov_b64_e32 v[0:1], s[10:11]
	s_and_saveexec_b64 s[6:7], vcc
	s_cbranch_execz .LBB0_273
	v_mov_b32_e32 v0, 0
	global_load_dword v1, v0, s[10:11] offset:-256 sc1
	s_mov_b64 s[16:17], 0
	s_waitcnt vmcnt(0)
	v_cmp_gt_u32_e32 vcc, v34, v1
	s_and_saveexec_b64 s[14:15], vcc
	s_cbranch_execz .LBB0_272
	s_add_u32 s12, s26, 0xfe00200
	s_addc_u32 s13, s27, 0
	s_mov_b32 s8, 1
	s_branch .LBB0_265

.LBB0_267:
	global_load_dword v1, v0, s[10:11] offset:-256 sc1
	s_add_i32 s8, s8, 1
	s_mov_b64 s[38:39], -1
	s_waitcnt vmcnt(0)
	v_cmp_le_u32_e32 vcc, v34, v1
	s_orn2_b64 s[42:43], vcc, exec
	s_branch .LBB0_264

.LBB0_420:
	global_load_dword v1, v0, s[10:11] offset:-256 sc1
	s_add_i32 s8, s8, 1
	s_mov_b64 s[20:21], -1
	s_waitcnt vmcnt(0)
	v_cmp_le_u32_e32 vcc, v34, v1
	s_orn2_b64 s[38:39], vcc, exec
	s_branch .LBB0_417

.LBB0_516:
	s_or_b64 exec, exec, s[12:13]
	v_cvt_f32_u32_e32 v3, v0
	s_waitcnt vmcnt(0)
	v_readfirstlane_b32 s6, v2
	s_add_u32 s12, s26, 0xfe03500
	s_addc_u32 s13, s27, 0
	v_rcp_iflag_f32_e32 v3, v3
	v_add_u32_e32 v1, s6, v1
	v_add_u32_e32 v4, 1, v1
	s_mov_b64 s[22:23], -1
	v_mul_f32_e32 v2, 0x4f7ffffe, v3
	v_cvt_u32_f32_e32 v2, v2
	v_sub_u32_e32 v3, 0, v0
	v_mul_lo_u32 v3, v3, v2
	v_mul_hi_u32 v3, v2, v3
	v_add_u32_e32 v2, v2, v3
	v_mul_hi_u32 v2, v1, v2
	v_mul_lo_u32 v3, v2, v0
	v_sub_u32_e32 v1, v1, v3
	v_add_u32_e32 v5, 1, v2
	v_cmp_ge_u32_e32 vcc, v1, v0
	v_sub_u32_e32 v3, v1, v0
	s_nop 0
	v_cndmask_b32_e32 v2, v2, v5, vcc
	v_cndmask_b32_e32 v1, v1, v3, vcc
	v_add_u32_e32 v3, 1, v2
	v_cmp_ge_u32_e32 vcc, v1, v0
	s_nop 1
	v_cndmask_b32_e32 v2, v2, v3, vcc
	v_mul_lo_u32 v1, v0, v2
	v_add_u32_e32 v0, v1, v0
	v_cmp_ne_u32_e32 vcc, v4, v0
	v_mov_b32_e32 v34, v0
	v_mov_b64_e32 v[0:1], s[12:13]
	s_and_saveexec_b64 s[6:7], vcc
	s_cbranch_execz .LBB0_528
	v_mov_b32_e32 v0, 0
	global_load_dword v1, v0, s[12:13] offset:-256 sc1
	s_mov_b64 s[40:41], 0
	s_waitcnt vmcnt(0)
	v_cmp_gt_u32_e32 vcc, v34, v1
	s_and_saveexec_b64 s[38:39], vcc
	s_cbranch_execz .LBB0_527
	s_add_u32 s22, s26, 0xfe00200
	s_addc_u32 s23, s27, 0
	s_mov_b32 s8, 1
	s_branch .LBB0_520

.LBB0_522:
	global_load_dword v1, v0, s[12:13] offset:-256 sc1
	s_add_i32 s8, s8, 1
	s_mov_b64 s[48:49], -1
	s_waitcnt vmcnt(0)
	v_cmp_le_u32_e32 vcc, v34, v1
	s_orn2_b64 s[56:57], vcc, exec
	s_branch .LBB0_519

.LBB0_571:
	s_or_b64 exec, exec, s[20:21]
	v_cvt_f32_u32_e32 v3, v0
	s_waitcnt vmcnt(0)
	v_readfirstlane_b32 s8, v2
	s_add_u32 s20, s26, 0xfe03500
	s_addc_u32 s21, s27, 0
	v_rcp_iflag_f32_e32 v3, v3
	v_add_u32_e32 v1, s8, v1
	v_add_u32_e32 v4, 1, v1
	s_mov_b64 s[22:23], -1
	v_mul_f32_e32 v2, 0x4f7ffffe, v3
	v_cvt_u32_f32_e32 v2, v2
	v_sub_u32_e32 v3, 0, v0
	v_mul_lo_u32 v3, v3, v2
	v_mul_hi_u32 v3, v2, v3
	v_add_u32_e32 v2, v2, v3
	v_mul_hi_u32 v2, v1, v2
	v_mul_lo_u32 v3, v2, v0
	v_sub_u32_e32 v1, v1, v3
	v_add_u32_e32 v5, 1, v2
	v_cmp_ge_u32_e32 vcc, v1, v0
	v_sub_u32_e32 v3, v1, v0
	s_nop 0
	v_cndmask_b32_e32 v2, v2, v5, vcc
	v_cndmask_b32_e32 v1, v1, v3, vcc
	v_add_u32_e32 v3, 1, v2
	v_cmp_ge_u32_e32 vcc, v1, v0
	s_nop 1
	v_cndmask_b32_e32 v2, v2, v3, vcc
	v_mul_lo_u32 v1, v0, v2
	v_add_u32_e32 v0, v1, v0
	v_cmp_ne_u32_e32 vcc, v4, v0
	v_mov_b32_e32 v34, v0
	v_mov_b64_e32 v[0:1], s[20:21]
	s_and_saveexec_b64 s[18:19], vcc
	s_cbranch_execz .LBB0_583
	v_mov_b32_e32 v0, 0
	global_load_dword v1, v0, s[20:21] offset:-256 sc1
	s_mov_b64 s[40:41], 0
	s_waitcnt vmcnt(0)
	v_cmp_gt_u32_e32 vcc, v34, v1
	s_and_saveexec_b64 s[38:39], vcc
	s_cbranch_execz .LBB0_582
	s_add_u32 s22, s26, 0xfe00200
	s_addc_u32 s23, s27, 0
	s_mov_b32 s8, 1
	s_branch .LBB0_575

.LBB0_577:
	global_load_dword v1, v0, s[20:21] offset:-256 sc1
	s_add_i32 s8, s8, 1
	s_mov_b64 s[48:49], -1
	s_waitcnt vmcnt(0)
	v_cmp_le_u32_e32 vcc, v34, v1
	s_orn2_b64 s[56:57], vcc, exec
	s_branch .LBB0_574

.LBB0_729:
	s_or_b64 exec, exec, s[16:17]
	v_cvt_f32_u32_e32 v3, v0
	s_waitcnt vmcnt(0)
	v_readfirstlane_b32 s8, v2
	s_add_u32 s16, s26, 0xfe03500
	s_addc_u32 s17, s27, 0
	v_rcp_iflag_f32_e32 v3, v3
	v_add_u32_e32 v1, s8, v1
	v_add_u32_e32 v4, 1, v1
	s_mov_b64 s[18:19], -1
	v_mul_f32_e32 v2, 0x4f7ffffe, v3
	v_cvt_u32_f32_e32 v2, v2
	v_sub_u32_e32 v3, 0, v0
	v_mul_lo_u32 v3, v3, v2
	v_mul_hi_u32 v3, v2, v3
	v_add_u32_e32 v2, v2, v3
	v_mul_hi_u32 v2, v1, v2
	v_mul_lo_u32 v3, v2, v0
	v_sub_u32_e32 v1, v1, v3
	v_add_u32_e32 v5, 1, v2
	v_cmp_ge_u32_e32 vcc, v1, v0
	v_sub_u32_e32 v3, v1, v0
	s_nop 0
	v_cndmask_b32_e32 v2, v2, v5, vcc
	v_cndmask_b32_e32 v1, v1, v3, vcc
	v_add_u32_e32 v3, 1, v2
	v_cmp_ge_u32_e32 vcc, v1, v0
	s_nop 1
	v_cndmask_b32_e32 v2, v2, v3, vcc
	v_mul_lo_u32 v1, v0, v2
	v_add_u32_e32 v0, v1, v0
	v_cmp_ne_u32_e32 vcc, v4, v0
	v_mov_b32_e32 v34, v0
	v_mov_b64_e32 v[0:1], s[16:17]
	s_and_saveexec_b64 s[12:13], vcc
	s_cbranch_execz .LBB0_741
	v_mov_b32_e32 v0, 0
	global_load_dword v1, v0, s[16:17] offset:-256 sc1
	s_mov_b64 s[22:23], 0
	s_waitcnt vmcnt(0)
	v_cmp_gt_u32_e32 vcc, v34, v1
	s_and_saveexec_b64 s[20:21], vcc
	s_cbranch_execz .LBB0_740
	s_add_u32 s18, s26, 0xfe00200
	s_addc_u32 s19, s27, 0
	s_mov_b32 s8, 1
	s_branch .LBB0_733

.LBB0_735:
	global_load_dword v1, v0, s[16:17] offset:-256 sc1
	s_add_i32 s8, s8, 1
	s_mov_b64 s[40:41], -1
	s_waitcnt vmcnt(0)
	v_cmp_le_u32_e32 vcc, v34, v1
	s_orn2_b64 s[44:45], vcc, exec
	s_branch .LBB0_732

.LBB0_794:
	global_load_dword v1, v0, s[20:21] offset:-256 sc1
	s_add_i32 s8, s8, 1
	s_mov_b64 s[44:45], -1
	s_waitcnt vmcnt(0)
	v_cmp_le_u32_e32 vcc, v34, v1
	s_orn2_b64 s[48:49], vcc, exec
	s_branch .LBB0_791

.LBB0_845:
	s_or_b64 exec, exec, s[22:23]
	v_cvt_f32_u32_e32 v3, v0
	s_waitcnt vmcnt(0)
	v_readfirstlane_b32 s3, v2
	s_add_u32 s22, s26, 0xfe03500
	s_addc_u32 s23, s27, 0
	v_rcp_iflag_f32_e32 v3, v3
	v_add_u32_e32 v1, s3, v1
	v_add_u32_e32 v4, 1, v1
	s_mov_b64 s[34:35], -1
	v_mul_f32_e32 v2, 0x4f7ffffe, v3
	v_cvt_u32_f32_e32 v2, v2
	v_sub_u32_e32 v3, 0, v0
	v_mul_lo_u32 v3, v3, v2
	v_mul_hi_u32 v3, v2, v3
	v_add_u32_e32 v2, v2, v3
	v_mul_hi_u32 v2, v1, v2
	v_mul_lo_u32 v3, v2, v0
	v_sub_u32_e32 v1, v1, v3
	v_add_u32_e32 v5, 1, v2
	v_cmp_ge_u32_e32 vcc, v1, v0
	v_sub_u32_e32 v3, v1, v0
	s_nop 0
	v_cndmask_b32_e32 v2, v2, v5, vcc
	v_cndmask_b32_e32 v1, v1, v3, vcc
	v_add_u32_e32 v3, 1, v2
	v_cmp_ge_u32_e32 vcc, v1, v0
	s_nop 1
	v_cndmask_b32_e32 v2, v2, v3, vcc
	v_mul_lo_u32 v1, v0, v2
	v_add_u32_e32 v0, v1, v0
	v_cmp_ne_u32_e32 vcc, v4, v0
	v_mov_b32_e32 v34, v0
	v_mov_b64_e32 v[0:1], s[22:23]
	s_and_saveexec_b64 s[20:21], vcc
	s_cbranch_execz .LBB0_857
	v_mov_b32_e32 v0, 0
	global_load_dword v1, v0, s[22:23] offset:-256 sc1
	s_mov_b64 s[40:41], 0
	s_waitcnt vmcnt(0)
	v_cmp_gt_u32_e32 vcc, v34, v1
	s_and_saveexec_b64 s[38:39], vcc
	s_cbranch_execz .LBB0_856
	s_add_u32 s34, s26, 0xfe00200
	s_addc_u32 s35, s27, 0
	s_mov_b32 s3, 1
	s_branch .LBB0_849

.LBB0_851:
	global_load_dword v1, v0, s[22:23] offset:-256 sc1
	s_add_i32 s3, s3, 1
	s_mov_b64 s[44:45], -1
	s_waitcnt vmcnt(0)
	v_cmp_le_u32_e32 vcc, v34, v1
	s_orn2_b64 s[48:49], vcc, exec
	s_branch .LBB0_848

.LBB0_906:
	s_or_b64 exec, exec, s[34:35]
	v_cvt_f32_u32_e32 v3, v0
	s_waitcnt vmcnt(0)
	v_readfirstlane_b32 s3, v2
	s_add_u32 s34, s26, 0xfe03500
	s_addc_u32 s35, s27, 0
	v_rcp_iflag_f32_e32 v3, v3
	v_add_u32_e32 v1, s3, v1
	v_add_u32_e32 v4, 1, v1
	s_mov_b64 s[38:39], -1
	v_mul_f32_e32 v2, 0x4f7ffffe, v3
	v_cvt_u32_f32_e32 v2, v2
	v_sub_u32_e32 v3, 0, v0
	v_mul_lo_u32 v3, v3, v2
	v_mul_hi_u32 v3, v2, v3
	v_add_u32_e32 v2, v2, v3
	v_mul_hi_u32 v2, v1, v2
	v_mul_lo_u32 v3, v2, v0
	v_sub_u32_e32 v1, v1, v3
	v_add_u32_e32 v5, 1, v2
	v_cmp_ge_u32_e32 vcc, v1, v0
	v_sub_u32_e32 v3, v1, v0
	s_nop 0
	v_cndmask_b32_e32 v2, v2, v5, vcc
	v_cndmask_b32_e32 v1, v1, v3, vcc
	v_add_u32_e32 v3, 1, v2
	v_cmp_ge_u32_e32 vcc, v1, v0
	s_nop 1
	v_cndmask_b32_e32 v2, v2, v3, vcc
	v_mul_lo_u32 v1, v0, v2
	v_add_u32_e32 v0, v1, v0
	v_cmp_ne_u32_e32 vcc, v4, v0
	v_mov_b32_e32 v34, v0
	v_mov_b64_e32 v[0:1], s[34:35]
	s_and_saveexec_b64 s[22:23], vcc
	s_cbranch_execz .LBB0_918
	v_mov_b32_e32 v0, 0
	global_load_dword v1, v0, s[34:35] offset:-256 sc1
	s_mov_b64 s[42:43], 0
	s_waitcnt vmcnt(0)
	v_cmp_gt_u32_e32 vcc, v34, v1
	s_and_saveexec_b64 s[40:41], vcc
	s_cbranch_execz .LBB0_917
	s_add_u32 s38, s26, 0xfe00200
	s_addc_u32 s39, s27, 0
	s_mov_b32 s3, 1
	s_branch .LBB0_910

.LBB0_912:
	global_load_dword v1, v0, s[34:35] offset:-256 sc1
	s_add_i32 s3, s3, 1
	s_mov_b64 s[46:47], -1
	s_waitcnt vmcnt(0)
	v_cmp_le_u32_e32 vcc, v34, v1
	s_orn2_b64 s[50:51], vcc, exec
	s_branch .LBB0_909

.LBB0_1114:
	s_or_b64 exec, exec, s[18:19]
	v_cvt_f32_u32_e32 v3, v0
	s_waitcnt vmcnt(0)
	v_readfirstlane_b32 s3, v2
	s_add_u32 s18, s26, 0xfe03500
	s_addc_u32 s19, s27, 0
	v_rcp_iflag_f32_e32 v3, v3
	v_add_u32_e32 v1, s3, v1
	v_add_u32_e32 v4, 1, v1
	s_mov_b64 s[20:21], -1
	v_mul_f32_e32 v2, 0x4f7ffffe, v3
	v_cvt_u32_f32_e32 v2, v2
	v_sub_u32_e32 v3, 0, v0
	v_mul_lo_u32 v3, v3, v2
	v_mul_hi_u32 v3, v2, v3
	v_add_u32_e32 v2, v2, v3
	v_mul_hi_u32 v2, v1, v2
	v_mul_lo_u32 v3, v2, v0
	v_sub_u32_e32 v1, v1, v3
	v_add_u32_e32 v5, 1, v2
	v_cmp_ge_u32_e32 vcc, v1, v0
	v_sub_u32_e32 v3, v1, v0
	s_nop 0
	v_cndmask_b32_e32 v2, v2, v5, vcc
	v_cndmask_b32_e32 v1, v1, v3, vcc
	v_add_u32_e32 v3, 1, v2
	v_cmp_ge_u32_e32 vcc, v1, v0
	s_nop 1
	v_cndmask_b32_e32 v2, v2, v3, vcc
	v_mul_lo_u32 v1, v0, v2
	v_add_u32_e32 v0, v1, v0
	v_cmp_ne_u32_e32 vcc, v4, v0
	v_mov_b32_e32 v34, v0
	v_mov_b64_e32 v[0:1], s[18:19]
	s_and_saveexec_b64 s[14:15], vcc
	s_cbranch_execz .LBB0_1126
	v_mov_b32_e32 v0, 0
	global_load_dword v1, v0, s[18:19] offset:-256 sc1
	s_mov_b64 s[34:35], 0
	s_waitcnt vmcnt(0)
	v_cmp_gt_u32_e32 vcc, v34, v1
	s_and_saveexec_b64 s[22:23], vcc
	s_cbranch_execz .LBB0_1125
	s_add_u32 s20, s26, 0xfe00200
	s_addc_u32 s21, s27, 0
	s_mov_b32 s3, 1
	s_branch .LBB0_1118

.LBB0_1120:
	global_load_dword v1, v0, s[18:19] offset:-256 sc1
	s_add_i32 s3, s3, 1
	s_mov_b64 s[40:41], -1
	s_waitcnt vmcnt(0)
	v_cmp_le_u32_e32 vcc, v34, v1
	s_orn2_b64 s[44:45], vcc, exec
	s_branch .LBB0_1117

.LBB0_1208:
	s_or_b64 exec, exec, s[18:19]
	v_cvt_f32_u32_e32 v3, v0
	s_waitcnt vmcnt(0)
	v_readfirstlane_b32 s3, v2
	s_add_u32 s18, s26, 0xfe03500
	s_addc_u32 s19, s27, 0
	v_rcp_iflag_f32_e32 v3, v3
	v_add_u32_e32 v1, s3, v1
	v_add_u32_e32 v4, 1, v1
	s_mov_b64 s[20:21], -1
	v_mul_f32_e32 v2, 0x4f7ffffe, v3
	v_cvt_u32_f32_e32 v2, v2
	v_sub_u32_e32 v3, 0, v0
	v_mul_lo_u32 v3, v3, v2
	v_mul_hi_u32 v3, v2, v3
	v_add_u32_e32 v2, v2, v3
	v_mul_hi_u32 v2, v1, v2
	v_mul_lo_u32 v3, v2, v0
	v_sub_u32_e32 v1, v1, v3
	v_add_u32_e32 v5, 1, v2
	v_cmp_ge_u32_e32 vcc, v1, v0
	v_sub_u32_e32 v3, v1, v0
	s_nop 0
	v_cndmask_b32_e32 v2, v2, v5, vcc
	v_cndmask_b32_e32 v1, v1, v3, vcc
	v_add_u32_e32 v3, 1, v2
	v_cmp_ge_u32_e32 vcc, v1, v0
	s_nop 1
	v_cndmask_b32_e32 v2, v2, v3, vcc
	v_mul_lo_u32 v1, v0, v2
	v_add_u32_e32 v0, v1, v0
	v_cmp_ne_u32_e32 vcc, v4, v0
	v_mov_b32_e32 v34, v0
	v_mov_b64_e32 v[0:1], s[18:19]
	s_and_saveexec_b64 s[16:17], vcc
	s_cbranch_execz .LBB0_1220
	v_mov_b32_e32 v0, 0
	global_load_dword v1, v0, s[18:19] offset:-256 sc1
	s_mov_b64 s[34:35], 0
	s_waitcnt vmcnt(0)
	v_cmp_gt_u32_e32 vcc, v34, v1
	s_and_saveexec_b64 s[22:23], vcc
	s_cbranch_execz .LBB0_1219
	s_add_u32 s20, s26, 0xfe00200
	s_addc_u32 s21, s27, 0
	s_mov_b32 s3, 1
	s_branch .LBB0_1212

.LBB0_1214:
	global_load_dword v1, v0, s[18:19] offset:-256 sc1
	s_add_i32 s3, s3, 1
	s_mov_b64 s[38:39], -1
	s_waitcnt vmcnt(0)
	v_cmp_le_u32_e32 vcc, v34, v1
	s_orn2_b64 s[42:43], vcc, exec
	s_branch .LBB0_1211

.LBB0_1276:
	s_or_b64 exec, exec, s[14:15]
	v_cvt_f32_u32_e32 v3, v0
	s_waitcnt vmcnt(0)
	v_readfirstlane_b32 s3, v2
	s_add_u32 s14, s26, 0xfe03500
	s_addc_u32 s15, s27, 0
	v_rcp_iflag_f32_e32 v3, v3
	v_add_u32_e32 v1, s3, v1
	v_add_u32_e32 v4, 1, v1
	s_mov_b64 s[16:17], -1
	v_mul_f32_e32 v2, 0x4f7ffffe, v3
	v_cvt_u32_f32_e32 v2, v2
	v_sub_u32_e32 v3, 0, v0
	v_mul_lo_u32 v3, v3, v2
	v_mul_hi_u32 v3, v2, v3
	v_add_u32_e32 v2, v2, v3
	v_mul_hi_u32 v2, v1, v2
	v_mul_lo_u32 v3, v2, v0
	v_sub_u32_e32 v1, v1, v3
	v_add_u32_e32 v5, 1, v2
	v_cmp_ge_u32_e32 vcc, v1, v0
	v_sub_u32_e32 v3, v1, v0
	s_nop 0
	v_cndmask_b32_e32 v2, v2, v5, vcc
	v_cndmask_b32_e32 v1, v1, v3, vcc
	v_add_u32_e32 v3, 1, v2
	v_cmp_ge_u32_e32 vcc, v1, v0
	s_nop 1
	v_cndmask_b32_e32 v2, v2, v3, vcc
	v_mul_lo_u32 v1, v0, v2
	v_add_u32_e32 v0, v1, v0
	v_cmp_ne_u32_e32 vcc, v4, v0
	v_mov_b32_e32 v34, v0
	v_mov_b64_e32 v[0:1], s[14:15]
	s_and_saveexec_b64 s[8:9], vcc
	s_cbranch_execz .LBB0_1288
	v_mov_b32_e32 v0, 0
	global_load_dword v1, v0, s[14:15] offset:-256 sc1
	s_mov_b64 s[20:21], 0
	s_waitcnt vmcnt(0)
	v_cmp_gt_u32_e32 vcc, v34, v1
	s_and_saveexec_b64 s[18:19], vcc
	s_cbranch_execz .LBB0_1287
	s_add_u32 s16, s26, 0xfe00200
	s_addc_u32 s17, s27, 0
	s_mov_b32 s3, 1
	s_branch .LBB0_1280

.LBB0_1282:
	global_load_dword v1, v0, s[14:15] offset:-256 sc1
	s_add_i32 s3, s3, 1
	s_mov_b64 s[30:31], -1
	s_waitcnt vmcnt(0)
	v_cmp_le_u32_e32 vcc, v34, v1
	s_orn2_b64 s[36:37], vcc, exec
	s_branch .LBB0_1279
